# prep T4 (sample K/V cache to bf16) fast path: fully unrolled, 64 loads in flight per lane, saddr addressing
# baseline (speedup 1.0000x reference)
.LBB0_253:
	s_waitcnt vmcnt(3)
	v_ashrrev_i32_e32 v0, 6, v206
	s_waitcnt vmcnt(2)
	v_and_b32_e32 v4, 63, v206
	v_cmp_lt_i32_e32 vcc, 5, v0
	s_and_saveexec_b64 s[2:3], vcc
	s_xor_b64 s[2:3], exec, s[2:3]
	s_cbranch_execz .LBB0_301
	v_lshl_add_u32 v0, s90, 7, v206
	v_add_u32_e32 v6, 0xfffffe80, v0
	s_lshl_b32 s4, s74, 7
	v_cmp_gt_i32_e32 vcc, s31, v6
	v_and_b32_e32 v2, 0x7f, v206
	v_ashrrev_i32_e32 v7, 31, v6
	s_and_saveexec_b64 s[6:7], vcc
	s_cbranch_execz .LBB0_271
	s_load_dwordx4 s[52:55], s[0:1], 0x10
	s_add_u32 s8, s72, 0xe9c8000
	s_addc_u32 s9, s73, 0
	s_waitcnt lgkmcnt(0)
	s_add_u32 s10, s72, 0xec48000
	s_addc_u32 s11, s73, 0
	s_lshl_b32 s12, s74, 10
	s_ashr_i32 s13, s12, 31
	v_lshl_add_u64 v[0:1], v[6:7], 2, s[52:53]
	s_lshl_b64 s[14:15], s[12:13], 2
	s_lshl_b32 s5, s74, 8
	s_lshl_b32 s13, s74, 9
	s_mov_b64 s[26:27], 0
	v_mov_b32_e32 v3, v6
	v_bfe_u32 v44, v6, 3, 3
	v_lshrrev_b32_e32 v45, 7, v6
	v_and_b32_e32 v45, 0x78, v45
	v_or_b32_e32 v44, v44, v45
	v_lshrrev_b32_e32 v45, 3, v6
	v_and_b32_e32 v45, 0x78, v45
	v_and_or_b32 v45, v6, 7, v45
	s_cmpk_lg_i32 s74, 0x100
	s_cbranch_scc1 .LBB0_257
	s_cmp_lg_u32 s31, 0x100000
	s_cbranch_scc1 .LBB0_257
	v_and_b32_e32 v3, 0x3fff, v6
	v_lshrrev_b32_e32 v5, 14, v6
	v_lshlrev_b32_e32 v0, 2, v6
	v_lshl_or_b32 v1, v44, 7, v45
	v_lshlrev_b32_e32 v1, 2, v1
	v_lshl_add_u32 v1, v5, 16, v1
	v_mul_u32_u24_e32 v5, 0xa000, v5
	v_lshl_add_u32 v3, v3, 1, v5
	v_mul_u32_u24_e32 v21, 0x140, v45
	v_lshl_add_u32 v21, v44, 1, v21
	v_add_u32_e32 v5, v5, v21
	s_mov_b64 s[38:39], s[52:53]
	s_mov_b64 s[40:41], s[54:55]
	s_mov_b64 s[44:45], s[8:9]
	s_mov_b64 s[46:47], s[10:11]
	global_load_dword v8, v0, s[38:39]
	global_load_dword v9, v1, s[40:41]
	s_add_u32 s38, s38, 0x20000
	s_addc_u32 s39, s39, 0
	s_add_u32 s40, s40, 0x20000
	s_addc_u32 s41, s41, 0
	global_load_dword v10, v0, s[38:39]
	global_load_dword v11, v1, s[40:41]
	s_add_u32 s38, s38, 0x20000
	s_addc_u32 s39, s39, 0
	s_add_u32 s40, s40, 0x20000
	s_addc_u32 s41, s41, 0
	global_load_dword v12, v0, s[38:39]
	global_load_dword v13, v1, s[40:41]
	s_add_u32 s38, s38, 0x20000
	s_addc_u32 s39, s39, 0
	s_add_u32 s40, s40, 0x20000
	s_addc_u32 s41, s41, 0
	global_load_dword v14, v0, s[38:39]
	global_load_dword v15, v1, s[40:41]
	s_add_u32 s38, s38, 0x20000
	s_addc_u32 s39, s39, 0
	s_add_u32 s40, s40, 0x20000
	s_addc_u32 s41, s41, 0
	global_load_dword v16, v0, s[38:39]
	global_load_dword v17, v1, s[40:41]
	s_add_u32 s38, s38, 0x20000
	s_addc_u32 s39, s39, 0
	s_add_u32 s40, s40, 0x20000
	s_addc_u32 s41, s41, 0
	global_load_dword v18, v0, s[38:39]
	global_load_dword v19, v1, s[40:41]
	s_add_u32 s38, s38, 0x20000
	s_addc_u32 s39, s39, 0
	s_add_u32 s40, s40, 0x20000
	s_addc_u32 s41, s41, 0
	global_load_dword v21, v0, s[38:39]
	global_load_dword v22, v1, s[40:41]
	s_add_u32 s38, s38, 0x20000
	s_addc_u32 s39, s39, 0
	s_add_u32 s40, s40, 0x20000
	s_addc_u32 s41, s41, 0
	global_load_dword v23, v0, s[38:39]
	global_load_dword v24, v1, s[40:41]
	s_add_u32 s38, s38, 0x20000
	s_addc_u32 s39, s39, 0
	s_add_u32 s40, s40, 0x20000
	s_addc_u32 s41, s41, 0
	global_load_dword v25, v0, s[38:39]
	global_load_dword v26, v1, s[40:41]
	s_add_u32 s38, s38, 0x20000
	s_addc_u32 s39, s39, 0
	s_add_u32 s40, s40, 0x20000
	s_addc_u32 s41, s41, 0
	global_load_dword v27, v0, s[38:39]
	global_load_dword v28, v1, s[40:41]
	s_add_u32 s38, s38, 0x20000
	s_addc_u32 s39, s39, 0
	s_add_u32 s40, s40, 0x20000
	s_addc_u32 s41, s41, 0
	global_load_dword v29, v0, s[38:39]
	global_load_dword v30, v1, s[40:41]
	s_add_u32 s38, s38, 0x20000
	s_addc_u32 s39, s39, 0
	s_add_u32 s40, s40, 0x20000
	s_addc_u32 s41, s41, 0
	global_load_dword v31, v0, s[38:39]
	global_load_dword v32, v1, s[40:41]
	s_add_u32 s38, s38, 0x20000
	s_addc_u32 s39, s39, 0
	s_add_u32 s40, s40, 0x20000
	s_addc_u32 s41, s41, 0
	global_load_dword v33, v0, s[38:39]
	global_load_dword v34, v1, s[40:41]
	s_add_u32 s38, s38, 0x20000
	s_addc_u32 s39, s39, 0
	s_add_u32 s40, s40, 0x20000
	s_addc_u32 s41, s41, 0
	global_load_dword v35, v0, s[38:39]
	global_load_dword v36, v1, s[40:41]
	s_add_u32 s38, s38, 0x20000
	s_addc_u32 s39, s39, 0
	s_add_u32 s40, s40, 0x20000
	s_addc_u32 s41, s41, 0
	global_load_dword v37, v0, s[38:39]
	global_load_dword v38, v1, s[40:41]
	s_add_u32 s38, s38, 0x20000
	s_addc_u32 s39, s39, 0
	s_add_u32 s40, s40, 0x20000
	s_addc_u32 s41, s41, 0
	global_load_dword v40, v0, s[38:39]
	global_load_dword v41, v1, s[40:41]
	s_add_u32 s38, s38, 0x20000
	s_addc_u32 s39, s39, 0
	s_add_u32 s40, s40, 0x20000
	s_addc_u32 s41, s41, 0
	s_waitcnt vmcnt(30)
	v_cvt_pk_bf16_f32 v8, v8, v20
	v_cvt_pk_bf16_f32 v9, v9, v20
	global_store_short v3, v8, s[44:45]
	global_store_short v5, v9, s[46:47]
	s_add_u32 s44, s44, 0x14000
	s_addc_u32 s45, s45, 0
	s_add_u32 s46, s46, 0x14000
	s_addc_u32 s47, s47, 0
	global_load_dword v8, v0, s[38:39]
	global_load_dword v9, v1, s[40:41]
	s_add_u32 s38, s38, 0x20000
	s_addc_u32 s39, s39, 0
	s_add_u32 s40, s40, 0x20000
	s_addc_u32 s41, s41, 0
	s_waitcnt vmcnt(32)
	v_cvt_pk_bf16_f32 v10, v10, v20
	v_cvt_pk_bf16_f32 v11, v11, v20
	global_store_short v3, v10, s[44:45]
	global_store_short v5, v11, s[46:47]
	s_add_u32 s44, s44, 0x14000
	s_addc_u32 s45, s45, 0
	s_add_u32 s46, s46, 0x14000
	s_addc_u32 s47, s47, 0
	global_load_dword v10, v0, s[38:39]
	global_load_dword v11, v1, s[40:41]
	s_add_u32 s38, s38, 0x20000
	s_addc_u32 s39, s39, 0
	s_add_u32 s40, s40, 0x20000
	s_addc_u32 s41, s41, 0
	s_waitcnt vmcnt(34)
	v_cvt_pk_bf16_f32 v12, v12, v20
	v_cvt_pk_bf16_f32 v13, v13, v20
	global_store_short v3, v12, s[44:45]
	global_store_short v5, v13, s[46:47]
	s_add_u32 s44, s44, 0x14000
	s_addc_u32 s45, s45, 0
	s_add_u32 s46, s46, 0x14000
	s_addc_u32 s47, s47, 0
	global_load_dword v12, v0, s[38:39]
	global_load_dword v13, v1, s[40:41]
	s_add_u32 s38, s38, 0x20000
	s_addc_u32 s39, s39, 0
	s_add_u32 s40, s40, 0x20000
	s_addc_u32 s41, s41, 0
	s_waitcnt vmcnt(36)
	v_cvt_pk_bf16_f32 v14, v14, v20
	v_cvt_pk_bf16_f32 v15, v15, v20
	global_store_short v3, v14, s[44:45]
	global_store_short v5, v15, s[46:47]
	s_add_u32 s44, s44, 0x14000
	s_addc_u32 s45, s45, 0
	s_add_u32 s46, s46, 0x14000
	s_addc_u32 s47, s47, 0
	global_load_dword v14, v0, s[38:39]
	global_load_dword v15, v1, s[40:41]
	s_add_u32 s38, s38, 0x20000
	s_addc_u32 s39, s39, 0
	s_add_u32 s40, s40, 0x20000
	s_addc_u32 s41, s41, 0
	s_waitcnt vmcnt(38)
	v_cvt_pk_bf16_f32 v16, v16, v20
	v_cvt_pk_bf16_f32 v17, v17, v20
	global_store_short v3, v16, s[44:45]
	global_store_short v5, v17, s[46:47]
	s_add_u32 s44, s44, 0x14000
	s_addc_u32 s45, s45, 0
	s_add_u32 s46, s46, 0x14000
	s_addc_u32 s47, s47, 0
	global_load_dword v16, v0, s[38:39]
	global_load_dword v17, v1, s[40:41]
	s_add_u32 s38, s38, 0x20000
	s_addc_u32 s39, s39, 0
	s_add_u32 s40, s40, 0x20000
	s_addc_u32 s41, s41, 0
	s_waitcnt vmcnt(40)
	v_cvt_pk_bf16_f32 v18, v18, v20
	v_cvt_pk_bf16_f32 v19, v19, v20
	global_store_short v3, v18, s[44:45]
	global_store_short v5, v19, s[46:47]
	s_add_u32 s44, s44, 0x14000
	s_addc_u32 s45, s45, 0
	s_add_u32 s46, s46, 0x14000
	s_addc_u32 s47, s47, 0
	global_load_dword v18, v0, s[38:39]
	global_load_dword v19, v1, s[40:41]
	s_add_u32 s38, s38, 0x20000
	s_addc_u32 s39, s39, 0
	s_add_u32 s40, s40, 0x20000
	s_addc_u32 s41, s41, 0
	s_waitcnt vmcnt(42)
	v_cvt_pk_bf16_f32 v21, v21, v20
	v_cvt_pk_bf16_f32 v22, v22, v20
	global_store_short v3, v21, s[44:45]
	global_store_short v5, v22, s[46:47]
	s_add_u32 s44, s44, 0x14000
	s_addc_u32 s45, s45, 0
	s_add_u32 s46, s46, 0x14000
	s_addc_u32 s47, s47, 0
	global_load_dword v21, v0, s[38:39]
	global_load_dword v22, v1, s[40:41]
	s_add_u32 s38, s38, 0x20000
	s_addc_u32 s39, s39, 0
	s_add_u32 s40, s40, 0x20000
	s_addc_u32 s41, s41, 0
	s_waitcnt vmcnt(44)
	v_cvt_pk_bf16_f32 v23, v23, v20
	v_cvt_pk_bf16_f32 v24, v24, v20
	global_store_short v3, v23, s[44:45]
	global_store_short v5, v24, s[46:47]
	s_add_u32 s44, s44, 0x14000
	s_addc_u32 s45, s45, 0
	s_add_u32 s46, s46, 0x14000
	s_addc_u32 s47, s47, 0
	global_load_dword v23, v0, s[38:39]
	global_load_dword v24, v1, s[40:41]
	s_add_u32 s38, s38, 0x20000
	s_addc_u32 s39, s39, 0
	s_add_u32 s40, s40, 0x20000
	s_addc_u32 s41, s41, 0
	s_waitcnt vmcnt(46)
	v_cvt_pk_bf16_f32 v25, v25, v20
	v_cvt_pk_bf16_f32 v26, v26, v20
	global_store_short v3, v25, s[44:45]
	global_store_short v5, v26, s[46:47]
	s_add_u32 s44, s44, 0x14000
	s_addc_u32 s45, s45, 0
	s_add_u32 s46, s46, 0x14000
	s_addc_u32 s47, s47, 0
	global_load_dword v25, v0, s[38:39]
	global_load_dword v26, v1, s[40:41]
	s_add_u32 s38, s38, 0x20000
	s_addc_u32 s39, s39, 0
	s_add_u32 s40, s40, 0x20000
	s_addc_u32 s41, s41, 0
	s_waitcnt vmcnt(48)
	v_cvt_pk_bf16_f32 v27, v27, v20
	v_cvt_pk_bf16_f32 v28, v28, v20
	global_store_short v3, v27, s[44:45]
	global_store_short v5, v28, s[46:47]
	s_add_u32 s44, s44, 0x14000
	s_addc_u32 s45, s45, 0
	s_add_u32 s46, s46, 0x14000
	s_addc_u32 s47, s47, 0
	global_load_dword v27, v0, s[38:39]
	global_load_dword v28, v1, s[40:41]
	s_add_u32 s38, s38, 0x20000
	s_addc_u32 s39, s39, 0
	s_add_u32 s40, s40, 0x20000
	s_addc_u32 s41, s41, 0
	s_waitcnt vmcnt(50)
	v_cvt_pk_bf16_f32 v29, v29, v20
	v_cvt_pk_bf16_f32 v30, v30, v20
	global_store_short v3, v29, s[44:45]
	global_store_short v5, v30, s[46:47]
	s_add_u32 s44, s44, 0x14000
	s_addc_u32 s45, s45, 0
	s_add_u32 s46, s46, 0x14000
	s_addc_u32 s47, s47, 0
	global_load_dword v29, v0, s[38:39]
	global_load_dword v30, v1, s[40:41]
	s_add_u32 s38, s38, 0x20000
	s_addc_u32 s39, s39, 0
	s_add_u32 s40, s40, 0x20000
	s_addc_u32 s41, s41, 0
	s_waitcnt vmcnt(52)
	v_cvt_pk_bf16_f32 v31, v31, v20
	v_cvt_pk_bf16_f32 v32, v32, v20
	global_store_short v3, v31, s[44:45]
	global_store_short v5, v32, s[46:47]
	s_add_u32 s44, s44, 0x14000
	s_addc_u32 s45, s45, 0
	s_add_u32 s46, s46, 0x14000
	s_addc_u32 s47, s47, 0
	global_load_dword v31, v0, s[38:39]
	global_load_dword v32, v1, s[40:41]
	s_add_u32 s38, s38, 0x20000
	s_addc_u32 s39, s39, 0
	s_add_u32 s40, s40, 0x20000
	s_addc_u32 s41, s41, 0
	s_waitcnt vmcnt(54)
	v_cvt_pk_bf16_f32 v33, v33, v20
	v_cvt_pk_bf16_f32 v34, v34, v20
	global_store_short v3, v33, s[44:45]
	global_store_short v5, v34, s[46:47]
	s_add_u32 s44, s44, 0x14000
	s_addc_u32 s45, s45, 0
	s_add_u32 s46, s46, 0x14000
	s_addc_u32 s47, s47, 0
	global_load_dword v33, v0, s[38:39]
	global_load_dword v34, v1, s[40:41]
	s_add_u32 s38, s38, 0x20000
	s_addc_u32 s39, s39, 0
	s_add_u32 s40, s40, 0x20000
	s_addc_u32 s41, s41, 0
	s_waitcnt vmcnt(56)
	v_cvt_pk_bf16_f32 v35, v35, v20
	v_cvt_pk_bf16_f32 v36, v36, v20
	global_store_short v3, v35, s[44:45]
	global_store_short v5, v36, s[46:47]
	s_add_u32 s44, s44, 0x14000
	s_addc_u32 s45, s45, 0
	s_add_u32 s46, s46, 0x14000
	s_addc_u32 s47, s47, 0
	global_load_dword v35, v0, s[38:39]
	global_load_dword v36, v1, s[40:41]
	s_add_u32 s38, s38, 0x20000
	s_addc_u32 s39, s39, 0
	s_add_u32 s40, s40, 0x20000
	s_addc_u32 s41, s41, 0
	s_waitcnt vmcnt(58)
	v_cvt_pk_bf16_f32 v37, v37, v20
	v_cvt_pk_bf16_f32 v38, v38, v20
	global_store_short v3, v37, s[44:45]
	global_store_short v5, v38, s[46:47]
	s_add_u32 s44, s44, 0x14000
	s_addc_u32 s45, s45, 0
	s_add_u32 s46, s46, 0x14000
	s_addc_u32 s47, s47, 0
	global_load_dword v37, v0, s[38:39]
	global_load_dword v38, v1, s[40:41]
	s_add_u32 s38, s38, 0x20000
	s_addc_u32 s39, s39, 0
	s_add_u32 s40, s40, 0x20000
	s_addc_u32 s41, s41, 0
	s_waitcnt vmcnt(60)
	v_cvt_pk_bf16_f32 v40, v40, v20
	v_cvt_pk_bf16_f32 v41, v41, v20
	global_store_short v3, v40, s[44:45]
	global_store_short v5, v41, s[46:47]
	s_add_u32 s44, s44, 0x14000
	s_addc_u32 s45, s45, 0
	s_add_u32 s46, s46, 0x14000
	s_addc_u32 s47, s47, 0
	global_load_dword v40, v0, s[38:39]
	global_load_dword v41, v1, s[40:41]
	s_waitcnt vmcnt(60)
	v_cvt_pk_bf16_f32 v8, v8, v20
	v_cvt_pk_bf16_f32 v9, v9, v20
	global_store_short v3, v8, s[44:45]
	global_store_short v5, v9, s[46:47]
	s_add_u32 s44, s44, 0x14000
	s_addc_u32 s45, s45, 0
	s_add_u32 s46, s46, 0x14000
	s_addc_u32 s47, s47, 0
	s_waitcnt vmcnt(58)
	v_cvt_pk_bf16_f32 v10, v10, v20
	v_cvt_pk_bf16_f32 v11, v11, v20
	global_store_short v3, v10, s[44:45]
	global_store_short v5, v11, s[46:47]
	s_add_u32 s44, s44, 0x14000
	s_addc_u32 s45, s45, 0
	s_add_u32 s46, s46, 0x14000
	s_addc_u32 s47, s47, 0
	s_waitcnt vmcnt(56)
	v_cvt_pk_bf16_f32 v12, v12, v20
	v_cvt_pk_bf16_f32 v13, v13, v20
	global_store_short v3, v12, s[44:45]
	global_store_short v5, v13, s[46:47]
	s_add_u32 s44, s44, 0x14000
	s_addc_u32 s45, s45, 0
	s_add_u32 s46, s46, 0x14000
	s_addc_u32 s47, s47, 0
	s_waitcnt vmcnt(54)
	v_cvt_pk_bf16_f32 v14, v14, v20
	v_cvt_pk_bf16_f32 v15, v15, v20
	global_store_short v3, v14, s[44:45]
	global_store_short v5, v15, s[46:47]
	s_add_u32 s44, s44, 0x14000
	s_addc_u32 s45, s45, 0
	s_add_u32 s46, s46, 0x14000
	s_addc_u32 s47, s47, 0
	s_waitcnt vmcnt(52)
	v_cvt_pk_bf16_f32 v16, v16, v20
	v_cvt_pk_bf16_f32 v17, v17, v20
	global_store_short v3, v16, s[44:45]
	global_store_short v5, v17, s[46:47]
	s_add_u32 s44, s44, 0x14000
	s_addc_u32 s45, s45, 0
	s_add_u32 s46, s46, 0x14000
	s_addc_u32 s47, s47, 0
	s_waitcnt vmcnt(50)
	v_cvt_pk_bf16_f32 v18, v18, v20
	v_cvt_pk_bf16_f32 v19, v19, v20
	global_store_short v3, v18, s[44:45]
	global_store_short v5, v19, s[46:47]
	s_add_u32 s44, s44, 0x14000
	s_addc_u32 s45, s45, 0
	s_add_u32 s46, s46, 0x14000
	s_addc_u32 s47, s47, 0
	s_waitcnt vmcnt(48)
	v_cvt_pk_bf16_f32 v21, v21, v20
	v_cvt_pk_bf16_f32 v22, v22, v20
	global_store_short v3, v21, s[44:45]
	global_store_short v5, v22, s[46:47]
	s_add_u32 s44, s44, 0x14000
	s_addc_u32 s45, s45, 0
	s_add_u32 s46, s46, 0x14000
	s_addc_u32 s47, s47, 0
	s_waitcnt vmcnt(46)
	v_cvt_pk_bf16_f32 v23, v23, v20
	v_cvt_pk_bf16_f32 v24, v24, v20
	global_store_short v3, v23, s[44:45]
	global_store_short v5, v24, s[46:47]
	s_add_u32 s44, s44, 0x14000
	s_addc_u32 s45, s45, 0
	s_add_u32 s46, s46, 0x14000
	s_addc_u32 s47, s47, 0
	s_waitcnt vmcnt(44)
	v_cvt_pk_bf16_f32 v25, v25, v20
	v_cvt_pk_bf16_f32 v26, v26, v20
	global_store_short v3, v25, s[44:45]
	global_store_short v5, v26, s[46:47]
	s_add_u32 s44, s44, 0x14000
	s_addc_u32 s45, s45, 0
	s_add_u32 s46, s46, 0x14000
	s_addc_u32 s47, s47, 0
	s_waitcnt vmcnt(42)
	v_cvt_pk_bf16_f32 v27, v27, v20
	v_cvt_pk_bf16_f32 v28, v28, v20
	global_store_short v3, v27, s[44:45]
	global_store_short v5, v28, s[46:47]
	s_add_u32 s44, s44, 0x14000
	s_addc_u32 s45, s45, 0
	s_add_u32 s46, s46, 0x14000
	s_addc_u32 s47, s47, 0
	s_waitcnt vmcnt(40)
	v_cvt_pk_bf16_f32 v29, v29, v20
	v_cvt_pk_bf16_f32 v30, v30, v20
	global_store_short v3, v29, s[44:45]
	global_store_short v5, v30, s[46:47]
	s_add_u32 s44, s44, 0x14000
	s_addc_u32 s45, s45, 0
	s_add_u32 s46, s46, 0x14000
	s_addc_u32 s47, s47, 0
	s_waitcnt vmcnt(38)
	v_cvt_pk_bf16_f32 v31, v31, v20
	v_cvt_pk_bf16_f32 v32, v32, v20
	global_store_short v3, v31, s[44:45]
	global_store_short v5, v32, s[46:47]
	s_add_u32 s44, s44, 0x14000
	s_addc_u32 s45, s45, 0
	s_add_u32 s46, s46, 0x14000
	s_addc_u32 s47, s47, 0
	s_waitcnt vmcnt(36)
	v_cvt_pk_bf16_f32 v33, v33, v20
	v_cvt_pk_bf16_f32 v34, v34, v20
	global_store_short v3, v33, s[44:45]
	global_store_short v5, v34, s[46:47]
	s_add_u32 s44, s44, 0x14000
	s_addc_u32 s45, s45, 0
	s_add_u32 s46, s46, 0x14000
	s_addc_u32 s47, s47, 0
	s_waitcnt vmcnt(34)
	v_cvt_pk_bf16_f32 v35, v35, v20
	v_cvt_pk_bf16_f32 v36, v36, v20
	global_store_short v3, v35, s[44:45]
	global_store_short v5, v36, s[46:47]
	s_add_u32 s44, s44, 0x14000
	s_addc_u32 s45, s45, 0
	s_add_u32 s46, s46, 0x14000
	s_addc_u32 s47, s47, 0
	s_waitcnt vmcnt(32)
	v_cvt_pk_bf16_f32 v37, v37, v20
	v_cvt_pk_bf16_f32 v38, v38, v20
	global_store_short v3, v37, s[44:45]
	global_store_short v5, v38, s[46:47]
	s_add_u32 s44, s44, 0x14000
	s_addc_u32 s45, s45, 0
	s_add_u32 s46, s46, 0x14000
	s_addc_u32 s47, s47, 0
	s_waitcnt vmcnt(30)
	v_cvt_pk_bf16_f32 v40, v40, v20
	v_cvt_pk_bf16_f32 v41, v41, v20
	global_store_short v3, v40, s[44:45]
	global_store_short v5, v41, s[46:47]
	s_branch .LBB0_271
